# kpost loop: k_norm gain loads hoisted out of the loop, rotary cos/sin loads issued at loop top with the K loads (one exposed latency per iteration instead of two)
# baseline (speedup 1.0000x reference)
; __device__ __forceinline__ int otid() { int t = threadIdx.x; asm volatile("" : "+v"(t)); return t; }
; __device__ __forceinline__ void kpost_phase(const bf16_t* qkv, const bf16_t* proj, const float* cstab, const float* kg, bf16_t* KF, int G) {
;     const int tid = otid(), sub = tid & 3;
;     for (int idx = (blockIdx.x * NTHR + tid) >> 2; idx < M * NH; idx += (G * NTHR) >> 2) {
;         const int tok = idx >> 3, h = idx & 7, b = tok / SEQ, s = tok & (SEQ - 1);
;         const bf16_t* s0 = qkv + (size_t)tok * 1792 + 768 + h * 128 + 8 * sub; const bf16_t* s1 = proj + (size_t)tok * 1024 + 384 + 8 * sub;
;         const float* cs = cstab + (size_t)tok * 32;
;         bf16_t* dst = KF + ((size_t)(b * NH + h) * SEQ + s) * 96 + 8 * sub;
.LBB0_979:
	s_or_b64 exec, exec, s[4:5]
	s_add_u32 s8, s74, 0x800000
	s_addc_u32 s9, s75, 0
	s_waitcnt lgkmcnt(0)
	s_barrier
	s_load_dwordx2 s[6:7], s[58:59], 0x68
	s_waitcnt lgkmcnt(0)
	v_mov_b32_e32 v4, v228
	s_add_u32 s10, s74, 0x20c00000
	s_mov_b32 s2, 0x200000
	v_add_u32_e32 v2, s56, v4
	s_addc_u32 s11, s75, 0
	v_cmp_gt_u32_e32 vcc, s2, v2
	s_and_saveexec_b64 s[4:5], vcc
	s_movk_i32 s14, 0xc0
	s_cbranch_execz .LBB0_982
	v_readlane_b32 s12, v254, 62
	v_readlane_b32 s13, v254, 63
	s_lshl_b64 s[12:13], s[12:13], 2
	v_bfe_u32 v11, v2, 2, 3
	s_add_u32 s6, s6, s12
	v_and_b32_e32 v3, 3, v4
	v_lshlrev_b32_e32 v4, 5, v4
	v_lshlrev_b32_e32 v6, 8, v11
	v_mov_b32_e32 v7, v65
	s_addc_u32 s7, s7, s13
	v_lshrrev_b32_e32 v10, 2, v2
	v_lshlrev_b32_e32 v64, 4, v3
	v_cmp_gt_u32_e32 vcc, 2, v3
	v_lshlrev_b32_e32 v2, 5, v3
	v_mov_b32_e32 v3, v65
	v_and_b32_e32 v4, 32, v4
	v_mov_b32_e32 v5, v65
	v_lshl_add_u64 v[6:7], s[80:81], 0, v[6:7]
	v_lshl_add_u64 v[0:1], s[10:11], 0, v[64:65]
	v_lshl_add_u64 v[2:3], s[6:7], 0, v[2:3]
	v_lshl_add_u64 v[4:5], s[8:9], 0, v[4:5]
	v_lshl_add_u64 v[6:7], v[6:7], 0, v[64:65]
	v_lshl_add_u64 v[8:9], s[0:1], 0, v[64:65]
	s_mov_b64 s[0:1], 0
	s_waitcnt vmcnt(0)
	global_load_dwordx4 v[156:159], v[2:3], off offset:144
	global_load_dwordx4 v[160:163], v[2:3], off offset:128
	global_load_dwordx4 v[164:167], v[2:3], off offset:16
	global_load_dwordx4 v[168:171], v[2:3], off
	global_load_dwordx4 v[172:175], v[2:3], off offset:272
	global_load_dwordx4 v[176:179], v[2:3], off offset:256
; template <int N> __device__ __forceinline__ float sxor(float v) { static_assert(N > 0 && N < 32, "sxor"); return __int_as_float(__builtin_amdgcn_ds_swizzle(__float_as_int(v), 0x1f | (N << 10))); }
; __device__ __forceinline__ u32x4 pack8(const float* v) { u32x4 w; w.x = cvt_pk_bf16(v[0], v[1]); w.y = cvt_pk_bf16(v[2], v[3]); w.z = cvt_pk_bf16(v[4], v[5]); w.w = cvt_pk_bf16(v[6], v[7]); return w; }
; __device__ __forceinline__ void kpost_phase(const bf16_t* qkv, const bf16_t* proj, const float* cstab, const float* kg, bf16_t* KF, int G) {
;     ...
;     for (int idx = (blockIdx.x * NTHR + tid) >> 2; idx < M * NH; idx += (G * NTHR) >> 2) {
;         const int tok = idx >> 3, h = idx & 7, b = tok / SEQ, s = tok & (SEQ - 1);
;         const bf16_t* s0 = qkv + (size_t)tok * 1792 + 768 + h * 128 + 8 * sub; const bf16_t* s1 = proj + (size_t)tok * 1024 + 384 + 8 * sub;
;         const float* cs = cstab + (size_t)tok * 32;
;         bf16_t* dst = KF + ((size_t)(b * NH + h) * SEQ + s) * 96 + 8 * sub;
;         const u32x4 r0 = *(const u32x4*)s0, r1 = *(const u32x4*)(s0 + 32), r2 = *(const u32x4*)s1;
;         float v0[8], v1[8], v2[8]; unpack8(r0, v0); unpack8(r1, v1); unpack8(r2, v2);
;         float ss = 0.f;
; #pragma unroll
;         for (int i = 0; i < 8; ++i) ss += v0[i] * v0[i] + v1[i] * v1[i] + v2[i] * v2[i];
;         ss += pg8::sxor<1>(ss); ss += pg8::sxor<2>(ss);
;         const float rs = __builtin_amdgcn_rsqf(ss * (1.0f / 96.0f) + EPS);
; #pragma unroll
;         for (int i = 0; i < 8; ++i) { v0[i] = v0[i] * rs * kg[8 * sub + i]; v1[i] = v1[i] * rs * kg[32 + 8 * sub + i]; v2[i] = v2[i] * rs * kg[64 + 8 * sub + i]; }
;         *(u32x4*)dst = pack8(v0); *(u32x4*)(dst + 32) = pack8(v1);
;         float o[8];
; #pragma unroll
;         for (int i = 0; i < 8; ++i) { const float other = pg8::sxor<2>(v2[i]); const int j = 8 * (sub & 1) + i; const float co = cs[j], si = cs[16 + j];
;             o[i] = (sub < 2) ? (v2[i] * co - other * si) : (other * si + v2[i] * co); }
;         *(u32x4*)(dst + 64) = pack8(o);
.LBB0_981:
	v_ashrrev_i32_e32 v48, 3, v10
	v_ashrrev_i32_e32 v36, 31, v10
	v_lshrrev_b32_e32 v44, 20, v36
	v_ashrrev_i32_e32 v49, 31, v48
	v_mad_i64_i32 v[40:41], s[6:7], v48, s85, v[6:7]
	global_load_dwordx4 v[36:39], v[40:41], off offset:1600
	s_nop 0
	global_load_dwordx4 v[40:43], v[40:41], off offset:1536
	v_add_u32_e32 v50, v48, v44
	v_lshlrev_b64 v[44:45], 11, v[48:49]
	v_lshlrev_b64 v[46:47], 7, v[48:49]
	v_lshl_add_u64 v[44:45], v[8:9], 0, v[44:45]
	v_ashrrev_i32_e32 v49, 12, v50
	v_lshl_add_u64 v[50:51], v[4:5], 0, v[46:47]
	global_load_dwordx4 v[44:47], v[44:45], off offset:768
	global_load_dwordx4 v[202:205], v[50:51], off offset:64
	global_load_dwordx4 v[206:209], v[50:51], off offset:80
	global_load_dwordx4 v[210:213], v[50:51], off
	global_load_dwordx4 v[214:217], v[50:51], off offset:16
	v_lshl_or_b32 v52, v49, 3, v11
	v_ashrrev_i32_e32 v53, 31, v52
	v_lshlrev_b64 v[52:53], 12, v[52:53]
	s_movk_i32 s2, 0xfff
	v_and_or_b32 v48, v48, s2, v52
	v_mad_u64_u32 v[48:49], s[6:7], v48, s14, v[0:1]
	v_mad_i32_i24 v49, v53, s14, v49
	v_add_u32_e32 v10, s61, v10
	s_mov_b32 s2, 0x7ffff
	v_cmp_lt_i32_e64 s[6:7], s2, v10
	s_or_b64 s[0:1], s[6:7], s[0:1]
	s_waitcnt vmcnt(6)
	v_lshlrev_b32_e32 v52, 16, v39
	v_and_b32_e32 v53, 0xffff0000, v39
	s_waitcnt vmcnt(5)
	v_lshlrev_b32_e32 v54, 16, v43
	v_and_b32_e32 v55, 0xffff0000, v43
	v_lshlrev_b32_e32 v56, 16, v38
	v_and_b32_e32 v57, 0xffff0000, v38
	v_lshlrev_b32_e32 v38, 16, v42
	v_and_b32_e32 v39, 0xffff0000, v42
	v_lshlrev_b32_e32 v42, 16, v37
	v_and_b32_e32 v43, 0xffff0000, v37
	v_lshlrev_b32_e32 v60, 16, v36
	v_and_b32_e32 v61, 0xffff0000, v36
	v_lshlrev_b32_e32 v58, 16, v41
	v_and_b32_e32 v59, 0xffff0000, v41
	v_lshlrev_b32_e32 v36, 16, v40
	v_and_b32_e32 v37, 0xffff0000, v40
	v_pk_mul_f32 v[62:63], v[56:57], v[56:57]
	v_pk_mul_f32 v[66:67], v[42:43], v[42:43]
	v_pk_mul_f32 v[68:69], v[60:61], v[60:61]
	s_waitcnt vmcnt(4)
	v_and_b32_e32 v71, 0xffff0000, v47
	v_lshlrev_b32_e32 v70, 16, v47
	v_and_b32_e32 v47, 0xffff0000, v46
	v_lshlrev_b32_e32 v46, 16, v46
	v_pk_fma_f32 v[62:63], v[38:39], v[38:39], v[62:63]
	v_and_b32_e32 v73, 0xffff0000, v45
	v_lshlrev_b32_e32 v72, 16, v45
	v_pk_fma_f32 v[66:67], v[58:59], v[58:59], v[66:67]
	v_pk_fma_f32 v[68:69], v[36:37], v[36:37], v[68:69]
	v_lshlrev_b32_e32 v74, 16, v44
	v_and_b32_e32 v75, 0xffff0000, v44
	v_pk_fma_f32 v[44:45], v[46:47], v[46:47], v[62:63]
	v_pk_fma_f32 v[62:63], v[72:73], v[72:73], v[66:67]
	v_pk_fma_f32 v[66:67], v[74:75], v[74:75], v[68:69]
	v_pk_mul_f32 v[40:41], v[52:53], v[52:53]
	v_add_f32_e32 v64, v66, v67
	v_add_f32_e32 v62, v62, v64
	v_add_f32_e32 v62, v63, v62
	v_pk_fma_f32 v[40:41], v[54:55], v[54:55], v[40:41]
	v_add_f32_e32 v44, v44, v62
	v_pk_fma_f32 v[40:41], v[70:71], v[70:71], v[40:41]
	v_add_f32_e32 v44, v45, v44
	v_add_f32_e32 v40, v40, v44
	v_add_f32_e32 v40, v41, v40
	ds_swizzle_b32 v41, v40 offset:swizzle(SWAP,1)
	s_waitcnt lgkmcnt(0)
	v_add_f32_e32 v40, v40, v41
	ds_swizzle_b32 v41, v40 offset:swizzle(SWAP,2)
	s_waitcnt lgkmcnt(0)
	v_add_f32_e32 v40, v40, v41
	v_fmamk_f32 v40, v40, 0x3c2aaaab, v232
	v_rsq_f32_e32 v40, v40
	s_nop 0
	v_pk_mul_f32 v[36:37], v[40:41], v[36:37] op_sel_hi:[0,1]
	v_pk_mul_f32 v[58:59], v[40:41], v[58:59] op_sel_hi:[0,1]
	v_pk_mul_f32 v[38:39], v[40:41], v[38:39] op_sel_hi:[0,1]
	v_pk_mul_f32 v[54:55], v[40:41], v[54:55] op_sel_hi:[0,1]
	v_pk_mul_f32 v[44:45], v[40:41], v[60:61] op_sel_hi:[0,1]
	v_pk_mul_f32 v[42:43], v[40:41], v[42:43] op_sel_hi:[0,1]
	v_pk_mul_f32 v[56:57], v[40:41], v[56:57] op_sel_hi:[0,1]
	v_pk_mul_f32 v[52:53], v[40:41], v[52:53] op_sel_hi:[0,1]
	v_pk_mul_f32 v[24:25], v[168:169], v[36:37]
	v_pk_mul_f32 v[26:27], v[170:171], v[58:59]
	v_pk_mul_f32 v[20:21], v[164:165], v[38:39]
	v_pk_mul_f32 v[22:23], v[54:55], v[166:167]
	v_pk_mul_f32 v[16:17], v[160:161], v[44:45]
	v_pk_mul_f32 v[18:19], v[162:163], v[42:43]
	v_pk_mul_f32 v[36:37], v[156:157], v[56:57]
	v_pk_mul_f32 v[38:39], v[52:53], v[158:159]
	v_cvt_pk_bf16_f32 v12, v24, v25
	v_cvt_pk_bf16_f32 v13, v26, v27
	v_cvt_pk_bf16_f32 v14, v20, v21
	v_cvt_pk_bf16_f32 v15, v22, v23
	v_cvt_pk_bf16_f32 v16, v16, v17
	v_cvt_pk_bf16_f32 v17, v18, v19
	v_cvt_pk_bf16_f32 v18, v36, v37
	v_cvt_pk_bf16_f32 v19, v38, v39
	global_store_dwordx4 v[48:49], v[12:15], off
	global_store_dwordx4 v[48:49], v[16:19], off offset:64
	s_nop 0
	v_pk_mul_f32 v[36:37], v[40:41], v[74:75] op_sel_hi:[0,1]
	v_pk_mul_f32 v[38:39], v[40:41], v[70:71] op_sel_hi:[0,1]
	v_pk_mul_f32 v[42:43], v[40:41], v[46:47] op_sel_hi:[0,1]
	v_pk_mul_f32 v[40:41], v[40:41], v[72:73] op_sel_hi:[0,1]
	v_pk_mul_f32 v[32:33], v[176:177], v[36:37]
	v_pk_mul_f32 v[30:31], v[38:39], v[174:175]
	v_pk_mul_f32 v[28:29], v[172:173], v[42:43]
	v_pk_mul_f32 v[34:35], v[178:179], v[40:41]
	ds_swizzle_b32 v36, v32 offset:swizzle(SWAP,2)
	ds_swizzle_b32 v37, v33 offset:swizzle(SWAP,2)
	ds_swizzle_b32 v38, v28 offset:swizzle(SWAP,2)
	ds_swizzle_b32 v39, v29 offset:swizzle(SWAP,2)
	ds_swizzle_b32 v40, v34 offset:swizzle(SWAP,2)
	ds_swizzle_b32 v41, v35 offset:swizzle(SWAP,2)
	ds_swizzle_b32 v42, v30 offset:swizzle(SWAP,2)
	ds_swizzle_b32 v43, v31 offset:swizzle(SWAP,2)
	s_waitcnt vmcnt(5) lgkmcnt(6)
	v_pk_mul_f32 v[12:13], v[202:203], v[36:37]
	s_waitcnt lgkmcnt(2)
	v_pk_mul_f32 v[14:15], v[204:205], v[40:41]
	s_waitcnt vmcnt(4)
	v_pk_mul_f32 v[16:17], v[206:207], v[38:39]
	s_waitcnt lgkmcnt(0)
	v_pk_mul_f32 v[18:19], v[208:209], v[42:43]
	v_cndmask_b32_e64 v13, v13, -v13, vcc
	v_cndmask_b32_e64 v12, v12, -v12, vcc
	v_cndmask_b32_e64 v15, v15, -v15, vcc
	v_cndmask_b32_e64 v14, v14, -v14, vcc
	v_cndmask_b32_e64 v17, v17, -v17, vcc
	v_cndmask_b32_e64 v16, v16, -v16, vcc
	v_cndmask_b32_e64 v19, v19, -v19, vcc
	v_cndmask_b32_e64 v18, v18, -v18, vcc
	s_waitcnt vmcnt(3)
	v_pk_fma_f32 v[12:13], v[32:33], v[210:211], v[12:13]
	v_pk_fma_f32 v[14:15], v[34:35], v[212:213], v[14:15]
	s_waitcnt vmcnt(2)
	v_pk_fma_f32 v[16:17], v[28:29], v[214:215], v[16:17]
	v_pk_fma_f32 v[18:19], v[30:31], v[216:217], v[18:19]
	v_cvt_pk_bf16_f32 v12, v12, v13
	v_cvt_pk_bf16_f32 v13, v14, v15
	v_cvt_pk_bf16_f32 v14, v16, v17
	v_cvt_pk_bf16_f32 v15, v18, v19
	global_store_dwordx4 v[48:49], v[12:15], off offset:128
	s_andn2_b64 exec, exec, s[0:1]
	s_cbranch_execnz .LBB0_981
